# baseline (speedup 1.0000x reference)
; __device__ __forceinline__ void nsa_quad(const Params& p, int qd, int g, float* slds, const int lane_in) {
;     ...
;     if (ncand <= ktarget) {
;       s0 = key0 != 0u; s1 = key1 != 0u; s2 = key2 != 0u; s3 = key3 != 0u;
;     } else {
;       unsigned T = 0u;
; #pragma unroll 1
;     ...
;         const unsigned cand = T | (1u << bit);
;         int cnt = __popcll(__ballot(key0 >= cand)) + __popcll(__ballot(key1 >= cand)) +
;                   __popcll(__ballot(key2 >= cand)) + __popcll(__ballot(key3 >= cand));
;         if (cnt >= ktarget) T = cand;
;       }
.LBB0_668:
	s_andn2_b64 vcc, exec, s[30:31]
	s_cbranch_vccnz .LBB0_684
	s_mov_b32 s16, 0
	s_mov_b32 s17, 30
	.p2align 6

; template <int NT, int BM, int BN, bool PLAIN, int NSTAGE, bool EPI_LDS>
; __device__ __forceinline__ void gemm_tile(const Params& p, const GemmDesc& g, bf16_t* lds, const int tid) {
;     ...
;   const int r0 = tid >> 3, c0 = tid & 7;
;   unsigned aoff[PLAIN ? 1 : NA];
;   const char* abase = (const char*)g.A;
;   if (PLAIN) {
;     abase = (const char*)(g.A + (long)m0 * g.lda_lo);
;     aoff[0] = (unsigned)((r0 * (int)g.lda_lo + c0 * 8) * 2);
;   } else {
; #pragma unroll
;     for (int i = 0; i < NA; ++i) {
;       int ra = m0 + r0 + RP * i;
;       int rlo = ra & g.rmask; rlo = rlo < g.rclamp ? rlo : g.rclamp;
;       aoff[i] = (unsigned)(((long)rlo * g.lda_lo + (long)(ra >> g.rshift) * g.lda_hi + c0 * 8) * 2);
;     }
;   }
;   const char* bbase = (const char*)(g.Bt + (long)n0 * g.ldb);
;   const unsigned boff = (unsigned)((r0 * (int)g.ldb + c0 * 8) * 2);
;   const long astepP = (long)RP * g.lda_lo * 2, bstepP = (long)RP * g.ldb * 2;
;   u32x4 ra4[NA], rb4[NB];
;   f32x4 acc[MI][NI];
; #pragma unroll
;   for (int i = 0; i < MI; ++i)
; #pragma unroll
;     for (int j = 0; j < NI; ++j) acc[i][j] = f32x4{0.f, 0.f, 0.f, 0.f};
;   const int nk = g.K >> 6;
;     ...
;   constexpr int STAGE_BYTES = (BM + BN) * 128;
;   char* const ldsb = (char*)lds;
;   const unsigned woff = (unsigned)(((r0 >> 4) * 2 + (c0 >> 2)) * 1024 + (((((r0 & 15) ^ (c0 >> 2)) * 64) + (c0 & 3) * 16) ^ (((r0 & 15) >> 3) << 5)));
;   const unsigned roff = (unsigned)(((fr * 64) + fq * 16) ^ ((fr >> 3) << 5));
;   const int roff1d = (int)((((fr ^ 1) * 64 + fq * 16) ^ ((fr >> 3) << 5))) - (int)roff;
;     ...
;     GLOAD(0)
;     __syncthreads();
;     LWRITE(0)
;     if (nk > 1) GLOAD(1)
;     __syncthreads();
.LBB0_896:
	v_lshrrev_b32_e32 v0, 6, v224
	v_and_b32_e32 v2, 63, v224
	v_readfirstlane_b32 s57, v0
	v_lshrrev_b32_e32 v3, 3, v2
	v_bfe_u32 v4, v2, 4, 2
	v_and_b32_e32 v5, 3, v2
	v_xor_b32_e32 v4, v4, v5
	v_lshlrev_b32_e32 v4, 4, v4
	v_bfe_u32 v5, v2, 2, 1
	v_lshl_or_b32 v4, v5, 6, v4
	v_xor_b32_e32 v5, 64, v4
	s_cmp_ge_u32 s57, 4
	s_cselect_b32 s58, s26, s52
	s_cselect_b32 s59, s41, s42
	s_cselect_b32 s60, s28, s30
	s_cselect_b32 s61, s29, s31
	s_and_b32 s62, s57, 3
	s_lshl_b32 s62, s62, 6
	s_add_i32 s59, s59, s62
	s_mul_i32 s59, s59, s58
	s_lshl_b32 s58, s58, 1
	s_lshl_b32 s59, s59, 1
	s_add_u32 s60, s60, s59
	s_addc_u32 s61, s61, 0
	v_mul_lo_u32 v3, v3, s58
	s_lshl_b32 s62, s58, 3
	v_add_u32_e32 v162, v3, v4
	v_add3_u32 v163, v3, v5, s62
	s_lshl_b32 s62, s58, 4
	v_add_u32_e32 v164, s62, v162
	v_add_u32_e32 v165, s62, v163
	v_add_u32_e32 v166, s62, v164
	v_add_u32_e32 v167, s62, v165
	v_add_u32_e32 v168, s62, v166
	v_add_u32_e32 v169, s62, v167
	s_lshl_b32 s57, s57, 13
	s_barrier
	s_mov_b32 m0, s57
	v_mov_b32_e32 v110, 0
	v_mov_b32_e32 v111, v110
	v_mov_b32_e32 v112, v110
	v_mov_b32_e32 v113, v110
	v_mov_b32_e32 v90, v110
	v_mov_b32_e32 v91, v110
	v_mov_b32_e32 v92, v110
	v_mov_b32_e32 v93, v110
	v_mov_b32_e32 v40, v110
	v_mov_b32_e32 v41, v110
	global_load_lds_dwordx4 v162, s[60:61]
	s_add_u32 m0, m0, 0x400
	v_mov_b32_e32 v42, v110
	v_mov_b32_e32 v43, v110
	v_mov_b32_e32 v44, v110
	v_mov_b32_e32 v45, v110
	v_mov_b32_e32 v46, v110
	v_mov_b32_e32 v47, v110
	v_mov_b32_e32 v48, v110
	v_mov_b32_e32 v49, v110
	v_mov_b32_e32 v50, v110
	v_mov_b32_e32 v51, v110
	global_load_lds_dwordx4 v163, s[60:61]
	s_add_u32 m0, m0, 0x400
	v_mov_b32_e32 v52, v110
	v_mov_b32_e32 v53, v110
	v_mov_b32_e32 v54, v110
	v_mov_b32_e32 v55, v110
	v_mov_b32_e32 v56, v110
	v_mov_b32_e32 v57, v110
	v_mov_b32_e32 v58, v110
	v_mov_b32_e32 v59, v110
	v_mov_b32_e32 v60, v110
	v_mov_b32_e32 v61, v110
	global_load_lds_dwordx4 v164, s[60:61]
	s_add_u32 m0, m0, 0x400
	v_mov_b32_e32 v62, v110
	v_mov_b32_e32 v63, v110
	v_mov_b32_e32 v64, v110
	v_mov_b32_e32 v65, v110
	v_mov_b32_e32 v66, v110
	v_mov_b32_e32 v67, v110
	v_mov_b32_e32 v68, v110
	v_mov_b32_e32 v69, v110
	v_mov_b32_e32 v70, v110
	v_mov_b32_e32 v71, v110
	global_load_lds_dwordx4 v165, s[60:61]
	s_add_u32 m0, m0, 0x400
	v_mov_b32_e32 v72, v110
	v_mov_b32_e32 v73, v110
	v_mov_b32_e32 v74, v110
	v_mov_b32_e32 v75, v110
	v_mov_b32_e32 v76, v110
	v_mov_b32_e32 v34, v110
	v_mov_b32_e32 v35, v110
	v_mov_b32_e32 v36, v110
	v_mov_b32_e32 v37, v110
	v_mov_b32_e32 v38, v110
	global_load_lds_dwordx4 v166, s[60:61]
	s_add_u32 m0, m0, 0x400
	v_mov_b32_e32 v39, v110
	v_mov_b32_e32 v77, v110
	v_mov_b32_e32 v78, v110
	v_mov_b32_e32 v79, v110
	v_mov_b32_e32 v80, v110
	v_mov_b32_e32 v81, v110
	v_mov_b32_e32 v82, v110
	v_mov_b32_e32 v83, v110
	v_mov_b32_e32 v84, v110
	v_mov_b32_e32 v85, v110
	global_load_lds_dwordx4 v167, s[60:61]
	s_add_u32 m0, m0, 0x400
	v_mov_b32_e32 v86, v110
	v_mov_b32_e32 v87, v110
	v_mov_b32_e32 v88, v110
	v_mov_b32_e32 v89, v110
	v_mov_b32_e32 v94, v110
	v_mov_b32_e32 v95, v110
	v_mov_b32_e32 v96, v110
	v_mov_b32_e32 v97, v110
	v_mov_b32_e32 v98, v110
	v_mov_b32_e32 v99, v110
	global_load_lds_dwordx4 v168, s[60:61]
	s_add_u32 m0, m0, 0x400
	v_mov_b32_e32 v100, v110
	v_mov_b32_e32 v101, v110
	v_mov_b32_e32 v102, v110
	v_mov_b32_e32 v103, v110
	v_mov_b32_e32 v104, v110
	v_mov_b32_e32 v105, v110
	v_mov_b32_e32 v106, v110
	v_mov_b32_e32 v107, v110
	v_mov_b32_e32 v108, v110
	v_mov_b32_e32 v109, v110
	global_load_lds_dwordx4 v169, s[60:61]
	s_add_u32 s60, s60, 0x80
	s_addc_u32 s61, s61, 0
	s_add_u32 m0, s57, 0x10000
	v_mov_b32_e32 v114, v110
	v_mov_b32_e32 v115, v110
	v_mov_b32_e32 v116, v110
	v_mov_b32_e32 v117, v110
	v_mov_b32_e32 v118, v110
	v_mov_b32_e32 v119, v110
	v_mov_b32_e32 v120, v110
	v_mov_b32_e32 v121, v110
	v_mov_b32_e32 v122, v110
	v_mov_b32_e32 v123, v110
	global_load_lds_dwordx4 v162, s[60:61]
	s_add_u32 m0, m0, 0x400
	v_mov_b32_e32 v124, v110
	v_mov_b32_e32 v125, v110
	v_mov_b32_e32 v126, v110
	v_mov_b32_e32 v127, v110
	v_mov_b32_e32 v128, v110
	v_mov_b32_e32 v129, v110
	v_mov_b32_e32 v130, v110
	v_mov_b32_e32 v131, v110
	v_mov_b32_e32 v132, v110
	v_mov_b32_e32 v133, v110
	global_load_lds_dwordx4 v163, s[60:61]
	s_add_u32 m0, m0, 0x400
	v_mov_b32_e32 v134, v110
	v_mov_b32_e32 v135, v110
	v_mov_b32_e32 v136, v110
	v_mov_b32_e32 v137, v110
	v_mov_b32_e32 v138, v110
	v_mov_b32_e32 v139, v110
	v_mov_b32_e32 v140, v110
	v_mov_b32_e32 v141, v110
	v_mov_b32_e32 v142, v110
	v_mov_b32_e32 v143, v110
	global_load_lds_dwordx4 v164, s[60:61]
	s_add_u32 m0, m0, 0x400
	v_mov_b32_e32 v144, v110
	v_mov_b32_e32 v145, v110
	v_mov_b32_e32 v146, v110
	v_mov_b32_e32 v147, v110
	v_mov_b32_e32 v148, v110
	v_mov_b32_e32 v149, v110
	v_mov_b32_e32 v150, v110
	v_mov_b32_e32 v151, v110
	v_mov_b32_e32 v152, v110
	v_mov_b32_e32 v153, v110
	global_load_lds_dwordx4 v165, s[60:61]
	v_mov_b32_e32 v154, v110
	v_mov_b32_e32 v155, v110
	v_mov_b32_e32 v156, v110
	v_mov_b32_e32 v157, v110
	v_mov_b32_e32 v158, v110
	v_mov_b32_e32 v159, v110
	v_mov_b32_e32 v160, v110
	v_mov_b32_e32 v161, v110
	s_add_i32 s3, s23, -2
	s_mov_b32 s26, 0
	s_mov_b32 s27, s3
	s_waitcnt vmcnt(4)
	s_barrier
	v_add_u32_e32 v19, v180, v184
	v_add_u32_e32 v18, v180, v183
	ds_read_b128 v[2:5], v19 offset:32768
	ds_read_b128 v[6:9], v19 offset:34816
	ds_read_b128 v[10:13], v19 offset:36864
	ds_read_b128 v[14:17], v19 offset:38912
	ds_read_b128 v[202:205], v18
	ds_read_b128 v[206:209], v18 offset:2048
	ds_read_b128 v[226:229], v18 offset:4096
	.p2align 6

; __device__ __forceinline__ float sigmoid_f(float x) { return 1.f / (1.f + __expf(-x)); }
; template <int NT, int BM, int BN, bool PLAIN, int NSTAGE, bool EPI_LDS>
; __device__ __forceinline__ void gemm_tile(const Params& p, const GemmDesc& g, bf16_t* lds, const int tid) {
;     ...
;       if (g.epi == E_MERGE0 || g.epi == E_MERGEN) {
;         const u32x4 gt = *(const u32x4*)(((bf16_t*)(p.ws + OFF_proj)) + (long)(m0e + row) * LDP + gcol + n0e + pc * 8);
;         u32x4 pv = u32x4{0u, 0u, 0u, 0u};
;         if (g.epi == E_MERGEN) pv = *(const u32x4*)op;
; #pragma unroll
;         for (int e = 0; e < 4; ++e) {
;           const float g0 = sigmoid_f(__uint_as_float(gt[e] << 16)), g1 = sigmoid_f(__uint_as_float(gt[e] & 0xffff0000u));
;           const float a0 = __uint_as_float(v[e] << 16), a1 = __uint_as_float(v[e] & 0xffff0000u);
;           const float p0 = __uint_as_float(pv[e] << 16), p1 = __uint_as_float(pv[e] & 0xffff0000u);
;           v[e] = pack2(p0 + g0 * a0, p1 + g1 * a1);
;         }
;       }
;       *(u32x4*)op = v;
.Lmy_merge0:
	v_lshrrev_b32_e32 v2, 5, v224
	v_and_b32_e32 v3, 31, v224
	v_lshlrev_b32_e32 v3, 4, v3
	v_mul_u32_u24_e32 v18, 0x210, v2
	v_add_u32_e32 v18, v18, v3
	v_add_u32_e32 v2, s23, v2
	v_mul_lo_u32 v160, v2, s48
	v_add_u32_e32 v160, v160, v3
	v_lshl_add_u32 v19, v2, 12, v3
	s_lshl_b32 s0, s24, 1
	s_add_u32 s60, s52, s0
	s_addc_u32 s61, s53, 0
	s_add_u32 s60, s60, 0x7cf6800
	s_addc_u32 s61, s61, 0
	s_mov_b64 s[62:63], s[26:27]
	s_mov_b64 s[64:65], s[26:27]
	v_mov_b32_e32 v16, 0
	v_mov_b32_e32 v17, 0
	global_load_dwordx4 v[186:189], v160, s[60:61]
	s_add_u32 s60, s60, 0x51000
	s_addc_u32 s61, s61, 0
	global_load_dwordx4 v[190:193], v160, s[60:61]
	s_add_u32 s60, s60, 0x51000
	s_addc_u32 s61, s61, 0
	global_load_dwordx4 v[194:197], v160, s[60:61]
	s_add_u32 s60, s60, 0x51000
	s_addc_u32 s61, s61, 0
	global_load_dwordx4 v[198:201], v160, s[60:61]
	s_add_u32 s60, s60, 0x51000
	s_addc_u32 s61, s61, 0
	s_mov_b32 s57, 0
	.p2align 6

; __device__ __forceinline__ float sigmoid_f(float x) { return 1.f / (1.f + __expf(-x)); }
; template <int NT, int BM, int BN, bool PLAIN, int NSTAGE, bool EPI_LDS>
; __device__ __forceinline__ void gemm_tile(const Params& p, const GemmDesc& g, bf16_t* lds, const int tid) {
;     ...
;       if (g.epi == E_MERGE0 || g.epi == E_MERGEN) {
;         const u32x4 gt = *(const u32x4*)(((bf16_t*)(p.ws + OFF_proj)) + (long)(m0e + row) * LDP + gcol + n0e + pc * 8);
;         u32x4 pv = u32x4{0u, 0u, 0u, 0u};
;         if (g.epi == E_MERGEN) pv = *(const u32x4*)op;
; #pragma unroll
;         for (int e = 0; e < 4; ++e) {
;           const float g0 = sigmoid_f(__uint_as_float(gt[e] << 16)), g1 = sigmoid_f(__uint_as_float(gt[e] & 0xffff0000u));
;           const float a0 = __uint_as_float(v[e] << 16), a1 = __uint_as_float(v[e] & 0xffff0000u);
;           const float p0 = __uint_as_float(pv[e] << 16), p1 = __uint_as_float(pv[e] & 0xffff0000u);
;           v[e] = pack2(p0 + g0 * a0, p1 + g1 * a1);
;         }
;       }
;       *(u32x4*)op = v;
.Lmy_mergeN:
	v_lshrrev_b32_e32 v2, 5, v224
	v_and_b32_e32 v3, 31, v224
	v_lshlrev_b32_e32 v3, 4, v3
	v_mul_u32_u24_e32 v18, 0x210, v2
	v_add_u32_e32 v18, v18, v3
	v_add_u32_e32 v2, s23, v2
	v_mul_lo_u32 v160, v2, s48
	v_add_u32_e32 v160, v160, v3
	v_lshl_add_u32 v19, v2, 12, v3
	s_lshl_b32 s0, s24, 1
	s_add_u32 s60, s52, s0
	s_addc_u32 s61, s53, 0
	s_add_u32 s60, s60, 0x7cf6800
	s_addc_u32 s61, s61, 0
	s_mov_b64 s[62:63], s[26:27]
	s_mov_b64 s[64:65], s[26:27]
	global_load_dwordx4 v[186:189], v160, s[60:61]
	global_load_dwordx4 v[226:229], v19, s[62:63]
	s_add_u32 s60, s60, 0x51000
	s_addc_u32 s61, s61, 0
	s_add_u32 s62, s62, 0x10000
	s_addc_u32 s63, s63, 0
	global_load_dwordx4 v[190:193], v160, s[60:61]
	global_load_dwordx4 v[230:233], v19, s[62:63]
	s_add_u32 s60, s60, 0x51000
	s_addc_u32 s61, s61, 0
	s_add_u32 s62, s62, 0x10000
	s_addc_u32 s63, s63, 0
	global_load_dwordx4 v[194:197], v160, s[60:61]
	global_load_dwordx4 v[234:237], v19, s[62:63]
	s_add_u32 s60, s60, 0x51000
	s_addc_u32 s61, s61, 0
	s_add_u32 s62, s62, 0x10000
	s_addc_u32 s63, s63, 0
	global_load_dwordx4 v[198:201], v160, s[60:61]
	global_load_dwordx4 v[238:241], v19, s[62:63]
	s_add_u32 s60, s60, 0x51000
	s_addc_u32 s61, s61, 0
	s_add_u32 s62, s62, 0x10000
	s_addc_u32 s63, s63, 0
	s_mov_b32 s57, 0
	.p2align 6
